# speedup vs baseline: 1.0009x; 1.0009x over previous
.LBB0_417:
	s_or_b64 exec, exec, s[16:17]
	s_waitcnt lgkmcnt(0)
	s_barrier
	ds_read_b128 v[156:159], v144
	s_waitcnt lgkmcnt(0)
	v_max_f32_e32 v152, v159, v159
	v_max_f32_e32 v154, v158, v158
	v_max_f32_e32 v152, v154, v152
	v_mov_b32_e32 v248, 0x3db8aa3b
	v_max3_f32 v152, v156, v157, v152
	v_mul_f32_e32 v152, 0x3db8aa3b, v152
	v_fma_f32 v154, v124, v248, -v152
	v_fma_f32 v156, v125, v248, -v152
	v_exp_f32_e32 v154, v154
	v_exp_f32_e32 v156, v156
	v_fma_f32 v157, v121, v248, -v152
	v_exp_f32_e32 v157, v157
	v_add_f32_e32 v154, v154, v156
	v_fma_f32 v156, v126, v248, -v152
	v_exp_f32_e32 v156, v156
	s_nop 0
	v_add_f32_e32 v154, v156, v154
	v_fma_f32 v156, v127, v248, -v152
	v_exp_f32_e32 v156, v156
	s_nop 0
	v_add_f32_e32 v154, v156, v154
	v_fma_f32 v156, v120, v248, -v152
	v_exp_f32_e32 v156, v156
	v_add_f32_e32 v154, 0, v154
	v_add_f32_e32 v156, v156, v157
	v_fma_f32 v157, v122, v248, -v152
	v_exp_f32_e32 v157, v157
	s_nop 0
	v_add_f32_e32 v156, v157, v156
	v_fma_f32 v157, v123, v248, -v152
	v_exp_f32_e32 v157, v157
	s_nop 0
	v_add_f32_e32 v156, v157, v156
	v_add_f32_e32 v154, v156, v154
	v_fma_f32 v156, v116, v248, -v152
	v_fma_f32 v157, v117, v248, -v152
	v_exp_f32_e32 v156, v156
	v_exp_f32_e32 v157, v157
	s_nop 0
	v_add_f32_e32 v156, v156, v157
	v_fma_f32 v157, v118, v248, -v152
	v_exp_f32_e32 v157, v157
	s_nop 0
	v_add_f32_e32 v156, v157, v156
	v_fma_f32 v157, v119, v248, -v152
	v_exp_f32_e32 v157, v157
	s_nop 0
	v_add_f32_e32 v156, v157, v156
	v_add_f32_e32 v154, v156, v154
	v_fma_f32 v156, v112, v248, -v152
	v_fma_f32 v157, v113, v248, -v152
	v_exp_f32_e32 v156, v156
	v_exp_f32_e32 v157, v157
	s_nop 0
	v_add_f32_e32 v156, v156, v157
	v_fma_f32 v157, v114, v248, -v152
	v_fma_f32 v152, v115, v248, -v152
	v_exp_f32_e32 v157, v157
	v_exp_f32_e32 v152, v152
	v_add_f32_e32 v156, v157, v156
	v_add_f32_e32 v152, v152, v156
	v_add_f32_e32 v152, v152, v154
	ds_bpermute_b32 v154, v146, v152
	s_waitcnt lgkmcnt(0)
	v_add_f32_e32 v152, v152, v154
	ds_bpermute_b32 v154, v148, v152
	s_and_saveexec_b64 s[16:17], vcc
	s_cbranch_execz .LBB0_419
	s_waitcnt lgkmcnt(0)
	v_add_f32_e32 v152, v152, v154
	ds_write_b32 v150, v152 offset:4096
.LBB0_419:
	s_or_b64 exec, exec, s[16:17]
	ds_read_b128 v[156:159], v144 offset:256
	s_waitcnt lgkmcnt(0)
	v_max_f32_e32 v152, v159, v159
	v_max_f32_e32 v154, v158, v158
	v_max_f32_e32 v152, v154, v152
	v_max3_f32 v152, v156, v157, v152
	v_mul_f32_e32 v152, 0x3db8aa3b, v152
	v_fma_f32 v154, v108, v248, -v152
	v_fma_f32 v156, v109, v248, -v152
	v_exp_f32_e32 v154, v154
	v_exp_f32_e32 v156, v156
	v_fma_f32 v157, v105, v248, -v152
	v_exp_f32_e32 v157, v157
	v_add_f32_e32 v154, v154, v156
	v_fma_f32 v156, v110, v248, -v152
	v_exp_f32_e32 v156, v156
	s_nop 0
	v_add_f32_e32 v154, v156, v154
	v_fma_f32 v156, v111, v248, -v152
	v_exp_f32_e32 v156, v156
	s_nop 0
	v_add_f32_e32 v154, v156, v154
	v_fma_f32 v156, v104, v248, -v152
	v_exp_f32_e32 v156, v156
	v_add_f32_e32 v154, 0, v154
	v_add_f32_e32 v156, v156, v157
	v_fma_f32 v157, v106, v248, -v152
	v_exp_f32_e32 v157, v157
	s_nop 0
	v_add_f32_e32 v156, v157, v156
	v_fma_f32 v157, v107, v248, -v152
	v_exp_f32_e32 v157, v157
	s_nop 0
	v_add_f32_e32 v156, v157, v156
	v_add_f32_e32 v154, v156, v154
	v_fma_f32 v156, v100, v248, -v152
	v_fma_f32 v157, v101, v248, -v152
	v_exp_f32_e32 v156, v156
	v_exp_f32_e32 v157, v157
	s_nop 0
	v_add_f32_e32 v156, v156, v157
	v_fma_f32 v157, v102, v248, -v152
	v_exp_f32_e32 v157, v157
	s_nop 0
	v_add_f32_e32 v156, v157, v156
	v_fma_f32 v157, v103, v248, -v152
	v_exp_f32_e32 v157, v157
	s_nop 0
	v_add_f32_e32 v156, v157, v156
	v_add_f32_e32 v154, v156, v154
	v_fma_f32 v156, v96, v248, -v152
	v_fma_f32 v157, v97, v248, -v152
	v_exp_f32_e32 v156, v156
	v_exp_f32_e32 v157, v157
	s_nop 0
	v_add_f32_e32 v156, v156, v157
	v_fma_f32 v157, v98, v248, -v152
	v_fma_f32 v152, v99, v248, -v152
	v_exp_f32_e32 v157, v157
	v_exp_f32_e32 v152, v152
	v_add_f32_e32 v156, v157, v156
	v_add_f32_e32 v152, v152, v156
	v_add_f32_e32 v152, v152, v154
	ds_bpermute_b32 v154, v146, v152
	s_waitcnt lgkmcnt(0)
	v_add_f32_e32 v152, v152, v154
	ds_bpermute_b32 v154, v148, v152
	s_and_saveexec_b64 s[16:17], vcc
	s_cbranch_execz .LBB0_421
	s_waitcnt lgkmcnt(0)
	v_add_f32_e32 v152, v152, v154
	ds_write_b32 v150, v152 offset:4352
.LBB0_421:
	s_or_b64 exec, exec, s[16:17]
	ds_read_b128 v[156:159], v144 offset:512
	s_waitcnt lgkmcnt(0)
	v_max_f32_e32 v152, v159, v159
	v_max_f32_e32 v154, v158, v158
	v_max_f32_e32 v152, v154, v152
	v_max3_f32 v152, v156, v157, v152
	v_mul_f32_e32 v152, 0x3db8aa3b, v152
	v_fma_f32 v154, v92, v248, -v152
	v_fma_f32 v156, v93, v248, -v152
	v_exp_f32_e32 v154, v154
	v_exp_f32_e32 v156, v156
	v_fma_f32 v157, v89, v248, -v152
	v_exp_f32_e32 v157, v157
	v_add_f32_e32 v154, v154, v156
	v_fma_f32 v156, v94, v248, -v152
	v_exp_f32_e32 v156, v156
	s_nop 0
	v_add_f32_e32 v154, v156, v154
	v_fma_f32 v156, v95, v248, -v152
	v_exp_f32_e32 v156, v156
	s_nop 0
	v_add_f32_e32 v154, v156, v154
	v_fma_f32 v156, v88, v248, -v152
	v_exp_f32_e32 v156, v156
	v_add_f32_e32 v154, 0, v154
	v_add_f32_e32 v156, v156, v157
	v_fma_f32 v157, v90, v248, -v152
	v_exp_f32_e32 v157, v157
	s_nop 0
	v_add_f32_e32 v156, v157, v156
	v_fma_f32 v157, v91, v248, -v152
	v_exp_f32_e32 v157, v157
	s_nop 0
	v_add_f32_e32 v156, v157, v156
	v_add_f32_e32 v154, v156, v154
	v_fma_f32 v156, v84, v248, -v152
	v_fma_f32 v157, v85, v248, -v152
	v_exp_f32_e32 v156, v156
	v_exp_f32_e32 v157, v157
	s_nop 0
	v_add_f32_e32 v156, v156, v157
	v_fma_f32 v157, v86, v248, -v152
	v_exp_f32_e32 v157, v157
	s_nop 0
	v_add_f32_e32 v156, v157, v156
	v_fma_f32 v157, v87, v248, -v152
	v_exp_f32_e32 v157, v157
	s_nop 0
	v_add_f32_e32 v156, v157, v156
	v_add_f32_e32 v154, v156, v154
	v_fma_f32 v156, v80, v248, -v152
	v_fma_f32 v157, v81, v248, -v152
	v_exp_f32_e32 v156, v156
	v_exp_f32_e32 v157, v157
	s_nop 0
	v_add_f32_e32 v156, v156, v157
	v_fma_f32 v157, v82, v248, -v152
	v_fma_f32 v152, v83, v248, -v152
	v_exp_f32_e32 v157, v157
	v_exp_f32_e32 v152, v152
	v_add_f32_e32 v156, v157, v156
	v_add_f32_e32 v152, v152, v156
	v_add_f32_e32 v152, v152, v154
	ds_bpermute_b32 v154, v146, v152
	s_waitcnt lgkmcnt(0)
	v_add_f32_e32 v152, v152, v154
	ds_bpermute_b32 v154, v148, v152
	s_and_saveexec_b64 s[16:17], vcc
	s_cbranch_execz .LBB0_423
	s_waitcnt lgkmcnt(0)
	v_add_f32_e32 v152, v152, v154
	ds_write_b32 v150, v152 offset:4608
.LBB0_423:
	s_or_b64 exec, exec, s[16:17]
	ds_read_b128 v[156:159], v144 offset:768
	s_waitcnt lgkmcnt(0)
	v_max_f32_e32 v152, v159, v159
	v_max_f32_e32 v154, v158, v158
	v_max_f32_e32 v152, v154, v152
	v_max3_f32 v152, v156, v157, v152
	v_mul_f32_e32 v152, 0x3db8aa3b, v152
	v_fma_f32 v154, v76, v248, -v152
	v_fma_f32 v156, v77, v248, -v152
	v_exp_f32_e32 v154, v154
	v_exp_f32_e32 v156, v156
	v_fma_f32 v157, v73, v248, -v152
	v_exp_f32_e32 v157, v157
	v_add_f32_e32 v154, v154, v156
	v_fma_f32 v156, v78, v248, -v152
	v_exp_f32_e32 v156, v156
	s_nop 0
	v_add_f32_e32 v154, v156, v154
	v_fma_f32 v156, v79, v248, -v152
	v_exp_f32_e32 v156, v156
	s_nop 0
	v_add_f32_e32 v154, v156, v154
	v_fma_f32 v156, v72, v248, -v152
	v_exp_f32_e32 v156, v156
	v_add_f32_e32 v154, 0, v154
	v_add_f32_e32 v156, v156, v157
	v_fma_f32 v157, v74, v248, -v152
	v_exp_f32_e32 v157, v157
	s_nop 0
	v_add_f32_e32 v156, v157, v156
	v_fma_f32 v157, v75, v248, -v152
	v_exp_f32_e32 v157, v157
	s_nop 0
	v_add_f32_e32 v156, v157, v156
	v_add_f32_e32 v154, v156, v154
	v_fma_f32 v156, v68, v248, -v152
	v_fma_f32 v157, v69, v248, -v152
	v_exp_f32_e32 v156, v156
	v_exp_f32_e32 v157, v157
	s_nop 0
	v_add_f32_e32 v156, v156, v157
	v_fma_f32 v157, v70, v248, -v152
	v_exp_f32_e32 v157, v157
	s_nop 0
	v_add_f32_e32 v156, v157, v156
	v_fma_f32 v157, v71, v248, -v152
	v_exp_f32_e32 v157, v157
	s_nop 0
	v_add_f32_e32 v156, v157, v156
	v_add_f32_e32 v154, v156, v154
	v_fma_f32 v156, v64, v248, -v152
	v_fma_f32 v157, v65, v248, -v152
	v_exp_f32_e32 v156, v156
	v_exp_f32_e32 v157, v157
	s_nop 0
	v_add_f32_e32 v156, v156, v157
	v_fma_f32 v157, v66, v248, -v152
	v_fma_f32 v152, v67, v248, -v152
	v_exp_f32_e32 v157, v157
	v_exp_f32_e32 v152, v152
	v_add_f32_e32 v156, v157, v156
	v_add_f32_e32 v152, v152, v156
	v_add_f32_e32 v152, v152, v154
	ds_bpermute_b32 v154, v146, v152
	s_waitcnt lgkmcnt(0)
	v_add_f32_e32 v152, v152, v154
	ds_bpermute_b32 v154, v148, v152
	s_and_saveexec_b64 s[16:17], vcc
	s_cbranch_execz .LBB0_425
	s_waitcnt lgkmcnt(0)
	v_add_f32_e32 v152, v152, v154
	ds_write_b32 v150, v152 offset:4864
.LBB0_425:
	s_or_b64 exec, exec, s[16:17]
	ds_read_b128 v[156:159], v144 offset:1024
	s_waitcnt lgkmcnt(0)
	v_max_f32_e32 v152, v159, v159
	v_max_f32_e32 v154, v158, v158
	v_max_f32_e32 v152, v154, v152
	v_max3_f32 v152, v156, v157, v152
	v_mul_f32_e32 v152, 0x3db8aa3b, v152
	v_fma_f32 v154, v60, v248, -v152
	v_fma_f32 v156, v61, v248, -v152
	v_exp_f32_e32 v154, v154
	v_exp_f32_e32 v156, v156
	v_fma_f32 v157, v57, v248, -v152
	v_exp_f32_e32 v157, v157
	v_add_f32_e32 v154, v154, v156
	v_fma_f32 v156, v62, v248, -v152
	v_exp_f32_e32 v156, v156
	s_nop 0
	v_add_f32_e32 v154, v156, v154
	v_fma_f32 v156, v63, v248, -v152
	v_exp_f32_e32 v156, v156
	s_nop 0
	v_add_f32_e32 v154, v156, v154
	v_fma_f32 v156, v56, v248, -v152
	v_exp_f32_e32 v156, v156
	v_add_f32_e32 v154, 0, v154
	v_add_f32_e32 v156, v156, v157
	v_fma_f32 v157, v58, v248, -v152
	v_exp_f32_e32 v157, v157
	s_nop 0
	v_add_f32_e32 v156, v157, v156
	v_fma_f32 v157, v59, v248, -v152
	v_exp_f32_e32 v157, v157
	s_nop 0
	v_add_f32_e32 v156, v157, v156
	v_add_f32_e32 v154, v156, v154
	v_fma_f32 v156, v52, v248, -v152
	v_fma_f32 v157, v53, v248, -v152
	v_exp_f32_e32 v156, v156
	v_exp_f32_e32 v157, v157
	s_nop 0
	v_add_f32_e32 v156, v156, v157
	v_fma_f32 v157, v54, v248, -v152
	v_exp_f32_e32 v157, v157
	s_nop 0
	v_add_f32_e32 v156, v157, v156
	v_fma_f32 v157, v55, v248, -v152
	v_exp_f32_e32 v157, v157
	s_nop 0
	v_add_f32_e32 v156, v157, v156
	v_add_f32_e32 v154, v156, v154
	v_fma_f32 v156, v48, v248, -v152
	v_fma_f32 v157, v49, v248, -v152
	v_exp_f32_e32 v156, v156
	v_exp_f32_e32 v157, v157
	s_nop 0
	v_add_f32_e32 v156, v156, v157
	v_fma_f32 v157, v50, v248, -v152
	v_fma_f32 v152, v51, v248, -v152
	v_exp_f32_e32 v157, v157
	v_exp_f32_e32 v152, v152
	v_add_f32_e32 v156, v157, v156
	v_add_f32_e32 v152, v152, v156
	v_add_f32_e32 v152, v152, v154
	ds_bpermute_b32 v154, v146, v152
	s_waitcnt lgkmcnt(0)
	v_add_f32_e32 v152, v152, v154
	ds_bpermute_b32 v154, v148, v152
	s_and_saveexec_b64 s[16:17], vcc
	s_cbranch_execz .LBB0_427
	s_waitcnt lgkmcnt(0)
	v_add_f32_e32 v152, v152, v154
	ds_write_b32 v150, v152 offset:5120
.LBB0_427:
	s_or_b64 exec, exec, s[16:17]
	ds_read_b128 v[156:159], v144 offset:1280
	s_waitcnt lgkmcnt(0)
	v_max_f32_e32 v152, v159, v159
	v_max_f32_e32 v154, v158, v158
	v_max_f32_e32 v152, v154, v152
	v_max3_f32 v152, v156, v157, v152
	v_mul_f32_e32 v152, 0x3db8aa3b, v152
	v_fma_f32 v154, v44, v248, -v152
	v_fma_f32 v156, v45, v248, -v152
	v_exp_f32_e32 v154, v154
	v_exp_f32_e32 v156, v156
	v_fma_f32 v157, v41, v248, -v152
	v_exp_f32_e32 v157, v157
	v_add_f32_e32 v154, v154, v156
	v_fma_f32 v156, v46, v248, -v152
	v_exp_f32_e32 v156, v156
	s_nop 0
	v_add_f32_e32 v154, v156, v154
	v_fma_f32 v156, v47, v248, -v152
	v_exp_f32_e32 v156, v156
	s_nop 0
	v_add_f32_e32 v154, v156, v154
	v_fma_f32 v156, v40, v248, -v152
	v_exp_f32_e32 v156, v156
	v_add_f32_e32 v154, 0, v154
	v_add_f32_e32 v156, v156, v157
	v_fma_f32 v157, v42, v248, -v152
	v_exp_f32_e32 v157, v157
	s_nop 0
	v_add_f32_e32 v156, v157, v156
	v_fma_f32 v157, v43, v248, -v152
	v_exp_f32_e32 v157, v157
	s_nop 0
	v_add_f32_e32 v156, v157, v156
	v_add_f32_e32 v154, v156, v154
	v_fma_f32 v156, v36, v248, -v152
	v_fma_f32 v157, v37, v248, -v152
	v_exp_f32_e32 v156, v156
	v_exp_f32_e32 v157, v157
	s_nop 0
	v_add_f32_e32 v156, v156, v157
	v_fma_f32 v157, v38, v248, -v152
	v_exp_f32_e32 v157, v157
	s_nop 0
	v_add_f32_e32 v156, v157, v156
	v_fma_f32 v157, v39, v248, -v152
	v_exp_f32_e32 v157, v157
	s_nop 0
	v_add_f32_e32 v156, v157, v156
	v_add_f32_e32 v154, v156, v154
	v_fma_f32 v156, v32, v248, -v152
	v_fma_f32 v157, v33, v248, -v152
	v_exp_f32_e32 v156, v156
	v_exp_f32_e32 v157, v157
	s_nop 0
	v_add_f32_e32 v156, v156, v157
	v_fma_f32 v157, v34, v248, -v152
	v_fma_f32 v152, v35, v248, -v152
	v_exp_f32_e32 v157, v157
	v_exp_f32_e32 v152, v152
	v_add_f32_e32 v156, v157, v156
	v_add_f32_e32 v152, v152, v156
	v_add_f32_e32 v152, v152, v154
	ds_bpermute_b32 v154, v146, v152
	s_waitcnt lgkmcnt(0)
	v_add_f32_e32 v152, v152, v154
	ds_bpermute_b32 v154, v148, v152
	s_and_saveexec_b64 s[16:17], vcc
	s_cbranch_execz .LBB0_429
	s_waitcnt lgkmcnt(0)
	v_add_f32_e32 v152, v152, v154
	ds_write_b32 v150, v152 offset:5376
.LBB0_429:
	s_or_b64 exec, exec, s[16:17]
	ds_read_b128 v[156:159], v144 offset:1536
	s_waitcnt lgkmcnt(0)
	v_max_f32_e32 v152, v159, v159
	v_max_f32_e32 v154, v158, v158
	v_max_f32_e32 v152, v154, v152
	v_max3_f32 v152, v156, v157, v152
	v_mul_f32_e32 v152, 0x3db8aa3b, v152
	v_fma_f32 v154, v28, v248, -v152
	v_fma_f32 v156, v29, v248, -v152
	v_exp_f32_e32 v154, v154
	v_exp_f32_e32 v156, v156
	v_fma_f32 v157, v25, v248, -v152
	v_exp_f32_e32 v157, v157
	v_add_f32_e32 v154, v154, v156
	v_fma_f32 v156, v30, v248, -v152
	v_exp_f32_e32 v156, v156
	s_nop 0
	v_add_f32_e32 v154, v156, v154
	v_fma_f32 v156, v31, v248, -v152
	v_exp_f32_e32 v156, v156
	s_nop 0
	v_add_f32_e32 v154, v156, v154
	v_fma_f32 v156, v24, v248, -v152
	v_exp_f32_e32 v156, v156
	v_add_f32_e32 v154, 0, v154
	v_add_f32_e32 v156, v156, v157
	v_fma_f32 v157, v26, v248, -v152
	v_exp_f32_e32 v157, v157
	s_nop 0
	v_add_f32_e32 v156, v157, v156
	v_fma_f32 v157, v27, v248, -v152
	v_exp_f32_e32 v157, v157
	s_nop 0
	v_add_f32_e32 v156, v157, v156
	v_add_f32_e32 v154, v156, v154
	v_fma_f32 v156, v20, v248, -v152
	v_fma_f32 v157, v21, v248, -v152
	v_exp_f32_e32 v156, v156
	v_exp_f32_e32 v157, v157
	s_nop 0
	v_add_f32_e32 v156, v156, v157
	v_fma_f32 v157, v22, v248, -v152
	v_exp_f32_e32 v157, v157
	s_nop 0
	v_add_f32_e32 v156, v157, v156
	v_fma_f32 v157, v23, v248, -v152
	v_exp_f32_e32 v157, v157
	s_nop 0
	v_add_f32_e32 v156, v157, v156
	v_add_f32_e32 v154, v156, v154
	v_fma_f32 v156, v16, v248, -v152
	v_fma_f32 v157, v17, v248, -v152
	v_exp_f32_e32 v156, v156
	v_exp_f32_e32 v157, v157
	s_nop 0
	v_add_f32_e32 v156, v156, v157
	v_fma_f32 v157, v18, v248, -v152
	v_fma_f32 v152, v19, v248, -v152
	v_exp_f32_e32 v157, v157
	v_exp_f32_e32 v152, v152
	v_add_f32_e32 v156, v157, v156
	v_add_f32_e32 v152, v152, v156
	v_add_f32_e32 v152, v152, v154
	ds_bpermute_b32 v154, v146, v152
	s_waitcnt lgkmcnt(0)
	v_add_f32_e32 v152, v152, v154
	ds_bpermute_b32 v154, v148, v152
	s_and_saveexec_b64 s[16:17], vcc
	s_cbranch_execz .LBB0_431
	s_waitcnt lgkmcnt(0)
	v_add_f32_e32 v152, v152, v154
	ds_write_b32 v150, v152 offset:5632
.LBB0_431:
	s_or_b64 exec, exec, s[16:17]
	ds_read_b128 v[156:159], v144 offset:1792
	s_waitcnt lgkmcnt(0)
	v_max_f32_e32 v152, v159, v159
	v_max_f32_e32 v154, v158, v158
	v_max_f32_e32 v152, v154, v152
	v_max3_f32 v152, v156, v157, v152
	v_mul_f32_e32 v152, 0x3db8aa3b, v152
	v_fma_f32 v154, v12, v248, -v152
	v_fma_f32 v156, v13, v248, -v152
	v_exp_f32_e32 v154, v154
	v_exp_f32_e32 v156, v156
	v_fma_f32 v157, v9, v248, -v152
	v_exp_f32_e32 v157, v157
	v_add_f32_e32 v154, v154, v156
	v_fma_f32 v156, v14, v248, -v152
	v_exp_f32_e32 v156, v156
	s_nop 0
	v_add_f32_e32 v154, v156, v154
	v_fma_f32 v156, v15, v248, -v152
	v_exp_f32_e32 v156, v156
	s_nop 0
	v_add_f32_e32 v154, v156, v154
	v_fma_f32 v156, v8, v248, -v152
	v_exp_f32_e32 v156, v156
	v_add_f32_e32 v154, 0, v154
	v_add_f32_e32 v156, v156, v157
	v_fma_f32 v157, v10, v248, -v152
	v_exp_f32_e32 v157, v157
	s_nop 0
	v_add_f32_e32 v156, v157, v156
	v_fma_f32 v157, v11, v248, -v152
	v_exp_f32_e32 v157, v157
	s_nop 0
	v_add_f32_e32 v156, v157, v156
	v_add_f32_e32 v154, v156, v154
	v_fma_f32 v156, v4, v248, -v152
	v_fma_f32 v157, v5, v248, -v152
	v_exp_f32_e32 v156, v156
	v_exp_f32_e32 v157, v157
	s_nop 0
	v_add_f32_e32 v156, v156, v157
	v_fma_f32 v157, v6, v248, -v152
	v_exp_f32_e32 v157, v157
	s_nop 0
	v_add_f32_e32 v156, v157, v156
	v_fma_f32 v157, v7, v248, -v152
	v_exp_f32_e32 v157, v157
	s_nop 0
	v_add_f32_e32 v156, v157, v156
	v_add_f32_e32 v154, v156, v154
	v_fma_f32 v156, v0, v248, -v152
	v_fma_f32 v157, v1, v248, -v152
	v_exp_f32_e32 v156, v156
	v_exp_f32_e32 v157, v157
	s_nop 0
	v_add_f32_e32 v156, v156, v157
	v_fma_f32 v157, v2, v248, -v152
	v_fma_f32 v152, v3, v248, -v152
	v_exp_f32_e32 v157, v157
	v_exp_f32_e32 v152, v152
	v_add_f32_e32 v156, v157, v156
	v_add_f32_e32 v152, v152, v156
	v_add_f32_e32 v152, v152, v154
	ds_bpermute_b32 v146, v146, v152
	s_waitcnt lgkmcnt(0)
	v_add_f32_e32 v146, v152, v146
	ds_bpermute_b32 v148, v148, v146
	s_and_saveexec_b64 s[16:17], vcc
	s_cbranch_execz .LBB0_433
	s_waitcnt lgkmcnt(0)
	v_add_f32_e32 v146, v146, v148
	ds_write_b32 v150, v146 offset:5888
.LBB0_433:
	s_or_b64 exec, exec, s[16:17]
	s_waitcnt lgkmcnt(0)
	s_barrier
	ds_read_b128 v[156:159], v144
	ds_read_b128 v[196:199], v144 offset:4096
	s_mov_b32 s18, s10
	s_mov_b32 s19, s11
	s_waitcnt lgkmcnt(0)
	v_max_f32_e32 v146, v159, v159
	v_max_f32_e32 v148, v158, v158
	v_max_f32_e32 v146, v148, v146
	v_max3_f32 v204, v156, v157, v146
	v_mul_f32_e32 v204, 0x3db8aa3b, v204
	v_add_f32_e32 v146, v196, v197
	v_add_f32_e32 v146, v198, v146
	v_add_f32_e32 v146, v199, v146
	v_div_scale_f32 v148, s[16:17], v146, v146, 1.0
	v_rcp_f32_e32 v150, v148
	ds_read_b128 v[196:199], v144 offset:256
	ds_read_b128 v[206:209], v144 offset:4352
	v_fma_f32 v152, -v148, v150, 1.0
	v_fmac_f32_e32 v150, v152, v150
	v_div_scale_f32 v152, vcc, 1.0, v146, 1.0
	v_mul_f32_e32 v154, v152, v150
	v_fma_f32 v156, -v148, v154, v152
	v_fmac_f32_e32 v154, v156, v150
	v_fma_f32 v148, -v148, v154, v152
	v_div_fmas_f32 v148, v148, v150, v154
	v_div_fixup_f32 v158, v148, v146, 1.0
	s_waitcnt lgkmcnt(0)
	v_max_f32_e32 v146, v199, v199
	v_max_f32_e32 v148, v198, v198
	v_max_f32_e32 v146, v148, v146
	v_max3_f32 v201, v196, v197, v146
	v_mul_f32_e32 v201, 0x3db8aa3b, v201
	v_add_f32_e32 v146, v206, v207
	v_add_f32_e32 v146, v208, v146
	v_add_f32_e32 v146, v209, v146
	v_div_scale_f32 v148, s[16:17], v146, v146, 1.0
	v_rcp_f32_e32 v150, v148
	ds_read_b128 v[196:199], v144 offset:512
	ds_read_b128 v[206:209], v144 offset:4608
	v_fma_f32 v152, -v148, v150, 1.0
	v_fmac_f32_e32 v150, v152, v150
	v_div_scale_f32 v152, vcc, 1.0, v146, 1.0
	v_mul_f32_e32 v154, v152, v150
	v_fma_f32 v156, -v148, v154, v152
	v_fmac_f32_e32 v154, v156, v150
	v_fma_f32 v148, -v148, v154, v152
	v_div_fmas_f32 v148, v148, v150, v154
	v_div_fixup_f32 v156, v148, v146, 1.0
	s_waitcnt lgkmcnt(0)
	v_max_f32_e32 v146, v199, v199
	v_max_f32_e32 v148, v198, v198
	v_max_f32_e32 v146, v148, v146
	v_max3_f32 v200, v196, v197, v146
	v_mul_f32_e32 v200, 0x3db8aa3b, v200
	v_add_f32_e32 v146, v206, v207
	v_add_f32_e32 v146, v208, v146
	v_add_f32_e32 v146, v209, v146
	v_div_scale_f32 v148, s[16:17], v146, v146, 1.0
	v_rcp_f32_e32 v150, v148
	ds_read_b128 v[196:199], v144 offset:768
	ds_read_b128 v[206:209], v144 offset:4864
	v_fma_f32 v152, -v148, v150, 1.0
	v_fmac_f32_e32 v150, v152, v150
	v_div_scale_f32 v152, vcc, 1.0, v146, 1.0
	v_mul_f32_e32 v154, v152, v150
	v_fma_f32 v157, -v148, v154, v152
	v_fmac_f32_e32 v154, v157, v150
	v_fma_f32 v148, -v148, v154, v152
	v_div_fmas_f32 v148, v148, v150, v154
	v_div_fixup_f32 v154, v148, v146, 1.0
	s_waitcnt lgkmcnt(0)
	v_max_f32_e32 v146, v199, v199
	v_max_f32_e32 v148, v198, v198
	v_max_f32_e32 v146, v148, v146
	v_max3_f32 v199, v196, v197, v146
	v_mul_f32_e32 v199, 0x3db8aa3b, v199
	v_add_f32_e32 v146, v206, v207
	v_add_f32_e32 v146, v208, v146
	v_add_f32_e32 v146, v209, v146
	v_div_scale_f32 v148, s[16:17], v146, v146, 1.0
	v_rcp_f32_e32 v150, v148
	ds_read_b128 v[206:209], v144 offset:1024
	ds_read_b128 v[210:213], v144 offset:5120
	v_fma_f32 v152, -v148, v150, 1.0
	v_fmac_f32_e32 v150, v152, v150
	v_div_scale_f32 v152, vcc, 1.0, v146, 1.0
	v_mul_f32_e32 v157, v152, v150
	v_fma_f32 v159, -v148, v157, v152
	v_fmac_f32_e32 v157, v159, v150
	v_fma_f32 v148, -v148, v157, v152
	v_div_fmas_f32 v148, v148, v150, v157
	v_div_fixup_f32 v152, v148, v146, 1.0
	s_waitcnt lgkmcnt(0)
	v_max_f32_e32 v146, v209, v209
	v_max_f32_e32 v148, v208, v208
	v_max_f32_e32 v146, v148, v146
	v_max3_f32 v198, v206, v207, v146
	v_mul_f32_e32 v198, 0x3db8aa3b, v198
	v_add_f32_e32 v146, v210, v211
	v_add_f32_e32 v146, v212, v146
	v_add_f32_e32 v146, v213, v146
	v_div_scale_f32 v148, s[16:17], v146, v146, 1.0
	v_rcp_f32_e32 v150, v148
	ds_read_b128 v[206:209], v144 offset:1280
	ds_read_b128 v[210:213], v144 offset:5376
	v_fma_f32 v157, -v148, v150, 1.0
	v_fmac_f32_e32 v150, v157, v150
	v_div_scale_f32 v157, vcc, 1.0, v146, 1.0
	v_mul_f32_e32 v159, v157, v150
	v_fma_f32 v160, -v148, v159, v157
	v_fmac_f32_e32 v159, v160, v150
	v_fma_f32 v148, -v148, v159, v157
	v_div_fmas_f32 v148, v148, v150, v159
	v_div_fixup_f32 v150, v148, v146, 1.0
	s_waitcnt lgkmcnt(0)
	v_max_f32_e32 v146, v209, v209
	v_max_f32_e32 v148, v208, v208
	v_max_f32_e32 v146, v148, v146
	v_max3_f32 v160, v206, v207, v146
	v_mul_f32_e32 v160, 0x3db8aa3b, v160
	v_add_f32_e32 v146, v210, v211
	v_add_f32_e32 v146, v212, v146
	v_add_f32_e32 v146, v213, v146
	v_div_scale_f32 v148, s[16:17], v146, v146, 1.0
	v_rcp_f32_e32 v157, v148
	ds_read_b128 v[206:209], v144 offset:1536
	ds_read_b128 v[210:213], v144 offset:5632
	v_fma_f32 v159, -v148, v157, 1.0
	v_fmac_f32_e32 v157, v159, v157
	v_div_scale_f32 v159, vcc, 1.0, v146, 1.0
	v_mul_f32_e32 v196, v159, v157
	v_fma_f32 v197, -v148, v196, v159
	v_fmac_f32_e32 v196, v197, v157
	v_fma_f32 v148, -v148, v196, v159
	v_div_fmas_f32 v148, v148, v157, v196
	v_div_fixup_f32 v148, v148, v146, 1.0
	s_waitcnt lgkmcnt(0)
	v_max_f32_e32 v146, v209, v209
	v_max_f32_e32 v157, v208, v208
	v_max_f32_e32 v146, v157, v146
	v_max3_f32 v159, v206, v207, v146
	v_mul_f32_e32 v159, 0x3db8aa3b, v159
	v_add_f32_e32 v146, v210, v211
	v_add_f32_e32 v146, v212, v146
	v_add_f32_e32 v146, v213, v146
	v_div_scale_f32 v157, s[16:17], v146, v146, 1.0
	v_rcp_f32_e32 v196, v157
	ds_read_b128 v[206:209], v144 offset:1792
	ds_read_b128 v[210:213], v144 offset:5888
	v_fma_f32 v197, -v157, v196, 1.0
	v_fmac_f32_e32 v196, v197, v196
	v_div_scale_f32 v197, vcc, 1.0, v146, 1.0
	v_mul_f32_e32 v202, v197, v196
	v_fma_f32 v203, -v157, v202, v197
	v_fmac_f32_e32 v202, v203, v196
	v_fma_f32 v157, -v157, v202, v197
	v_div_fmas_f32 v157, v157, v196, v202
	v_div_fixup_f32 v146, v157, v146, 1.0
	s_waitcnt lgkmcnt(0)
; __device__ __forceinline__ uint2 pk4(const f32x4& v) { uint2 r; r.x = pk2(v[0], v[1]); r.y = pk2(v[2], v[3]); return r; }
; template <class F>
; __device__ __forceinline__ void epi_store_bf16(f32x4 (&acc)[8][4], bf16* C, int ldc, int wr, int wc, int fr, int fq, F f) {
;   char* slab = g_shm + 65536 + (wr * 4 + wc) * 8192;
;   const int lane = (fq << 4) | fr;
;   const int rr = lane >> 3, kk = lane & 7;
;   const unsigned go = (unsigned)((wr * 128 + rr) * ldc + wc * 64 + kk * 8);
;   const __amdgpu_buffer_rsrc_t rsrc = __builtin_amdgcn_make_buffer_rsrc((void*)C, (short)0, 0x7fffffff, 0x27000);
; #pragma unroll
;   for (int half = 0; half < 2; ++half) {
; #pragma unroll
;     for (int mm = 0; mm < 4; ++mm)
; #pragma unroll
;       for (int n = 0; n < 4; ++n)
;         *(uint2*)(slab + (mm * 16 + fr) * 128 + (((n * 4 + fq) ^ (fr & 14)) << 3)) = pk4(f(acc[half * 4 + mm][n], half * 4 + mm, n));
	v_max_f32_e32 v144, v209, v209
	v_max_f32_e32 v157, v208, v208
	v_max_f32_e32 v144, v157, v144
	v_max3_f32 v157, v206, v207, v144
	v_mul_f32_e32 v157, 0x3db8aa3b, v157
	v_add_f32_e32 v144, v210, v211
	v_add_f32_e32 v144, v212, v144
	v_add_f32_e32 v144, v213, v144
	v_div_scale_f32 v196, s[16:17], v144, v144, 1.0
	v_rcp_f32_e32 v197, v196
	s_and_b32 s17, s13, 0xffff
	s_mov_b32 s16, s12
	v_fma_f32 v202, -v196, v197, 1.0
	v_fmac_f32_e32 v197, v202, v197
	v_div_scale_f32 v202, vcc, 1.0, v144, 1.0
	v_mul_f32_e32 v203, v202, v197
	v_fma_f32 v205, -v196, v203, v202
	v_fmac_f32_e32 v203, v205, v197
	v_fma_f32 v196, -v196, v203, v202
	v_div_fmas_f32 v196, v196, v197, v203
	v_div_fixup_f32 v144, v196, v144, 1.0
	v_lshlrev_b32_e32 v196, 15, v155
	v_lshlrev_b32_e32 v197, 13, v147
	v_add3_u32 v202, v196, v197, s89
	v_ashrrev_i32_e32 v203, 3, v153
	v_lshlrev_b32_e32 v205, 18, v155
	v_lshl_add_u32 v155, v203, 7, v202
	v_xor_b32_e32 v153, v153, v145
	v_and_or_b32 v153, v153, s44, v155
	v_fma_f32 v155, v124, v248, -v204
	v_exp_f32_e32 v196, v155
	v_fma_f32 v155, v125, v248, -v204
	v_exp_f32_e32 v197, v155
	v_fma_f32 v155, v126, v248, -v204
	v_exp_f32_e32 v206, v155
	v_fma_f32 v155, v127, v248, -v204
	v_exp_f32_e32 v207, v155
	v_lshl_add_u32 v210, v149, 7, v202
	v_pk_mul_f32 v[196:197], v[158:159], v[196:197] op_sel_hi:[0,1]
	v_bitop3_b32 v155, v149, v151, 14 bitop3:0x6c
	v_pk_mul_f32 v[206:207], v[158:159], v[206:207] op_sel_hi:[0,1]
	v_cvt_pk_bf16_f32 v196, v196, v197
	v_cvt_pk_bf16_f32 v197, v206, v207
	v_lshl_add_u32 v155, v155, 3, v210
	s_waitcnt vmcnt(0)
	ds_write_b64 v155, v[196:197]
	v_fma_f32 v196, v120, v248, -v204
	v_fma_f32 v197, v121, v248, -v204
	v_exp_f32_e32 v196, v196
	v_exp_f32_e32 v197, v197
	v_fma_f32 v206, v122, v248, -v204
	v_fma_f32 v207, v123, v248, -v204
	v_exp_f32_e32 v206, v206
	v_exp_f32_e32 v207, v207
	v_pk_mul_f32 v[196:197], v[158:159], v[196:197] op_sel_hi:[0,1]
	v_cvt_pk_bf16_f32 v208, v196, v197
	v_fma_f32 v197, v116, v248, -v204
	v_pk_mul_f32 v[206:207], v[158:159], v[206:207] op_sel_hi:[0,1]
	v_cvt_pk_bf16_f32 v209, v206, v207
	v_exp_f32_e32 v206, v197
	v_fma_f32 v197, v117, v248, -v204
	v_add_u32_e32 v196, 4, v151
	v_bitop3_b32 v196, v196, v149, 14 bitop3:0x78
	v_exp_f32_e32 v207, v197
	v_fma_f32 v197, v118, v248, -v204
	v_lshl_add_u32 v196, v196, 3, v210
	ds_write_b64 v196, v[208:209]
	v_exp_f32_e32 v208, v197
	v_fma_f32 v197, v119, v248, -v204
	v_exp_f32_e32 v209, v197
	v_add_u32_e32 v197, 8, v151
	v_pk_mul_f32 v[206:207], v[158:159], v[206:207] op_sel_hi:[0,1]
	v_bitop3_b32 v197, v197, v149, 14 bitop3:0x78
	v_pk_mul_f32 v[208:209], v[158:159], v[208:209] op_sel_hi:[0,1]
	v_cvt_pk_bf16_f32 v206, v206, v207
	v_cvt_pk_bf16_f32 v207, v208, v209
	v_lshl_add_u32 v197, v197, 3, v210
	ds_write_b64 v197, v[206:207]
	v_fma_f32 v206, v112, v248, -v204
	v_fma_f32 v207, v113, v248, -v204
	v_fma_f32 v208, v114, v248, -v204
	v_fma_f32 v204, v115, v248, -v204
	v_exp_f32_e32 v206, v206
	v_exp_f32_e32 v207, v207
	v_exp_f32_e32 v208, v208
	v_exp_f32_e32 v209, v204
	v_add_u32_e32 v151, 12, v151
	v_pk_mul_f32 v[206:207], v[158:159], v[206:207] op_sel_hi:[0,1]
	v_bitop3_b32 v149, v151, v149, 14 bitop3:0x78
	v_pk_mul_f32 v[208:209], v[158:159], v[208:209] op_sel_hi:[0,1]
	v_fma_f32 v151, v108, v248, -v201
	v_cvt_pk_bf16_f32 v206, v206, v207
	v_cvt_pk_bf16_f32 v207, v208, v209
	v_lshl_add_u32 v149, v149, 3, v210
	ds_write_b64 v149, v[206:207]
	v_exp_f32_e32 v206, v151
	v_fma_f32 v151, v109, v248, -v201
	v_exp_f32_e32 v207, v151
	v_fma_f32 v151, v110, v248, -v201
	v_exp_f32_e32 v208, v151
	v_fma_f32 v151, v111, v248, -v201
	v_exp_f32_e32 v209, v151
	v_pk_mul_f32 v[206:207], v[156:157], v[206:207] op_sel_hi:[0,1]
	v_fma_f32 v151, v104, v248, -v201
	v_cvt_pk_bf16_f32 v206, v206, v207
	v_pk_mul_f32 v[208:209], v[156:157], v[208:209] op_sel_hi:[0,1]
	v_cvt_pk_bf16_f32 v207, v208, v209
	ds_write_b64 v155, v[206:207] offset:2048
	v_exp_f32_e32 v206, v151
	v_fma_f32 v151, v105, v248, -v201
	v_exp_f32_e32 v207, v151
	v_fma_f32 v151, v106, v248, -v201
	v_exp_f32_e32 v208, v151
	v_fma_f32 v151, v107, v248, -v201
	v_exp_f32_e32 v209, v151
	v_pk_mul_f32 v[206:207], v[156:157], v[206:207] op_sel_hi:[0,1]
	v_fma_f32 v151, v100, v248, -v201
	v_cvt_pk_bf16_f32 v206, v206, v207
	v_pk_mul_f32 v[208:209], v[156:157], v[208:209] op_sel_hi:[0,1]
	v_cvt_pk_bf16_f32 v207, v208, v209
	ds_write_b64 v196, v[206:207] offset:2048
	v_exp_f32_e32 v206, v151
	v_fma_f32 v151, v101, v248, -v201
	v_exp_f32_e32 v207, v151
	v_fma_f32 v151, v102, v248, -v201
	v_exp_f32_e32 v208, v151
	v_fma_f32 v151, v103, v248, -v201
	v_exp_f32_e32 v209, v151
	v_pk_mul_f32 v[206:207], v[156:157], v[206:207] op_sel_hi:[0,1]
	v_fma_f32 v151, v96, v248, -v201
	v_cvt_pk_bf16_f32 v206, v206, v207
	v_pk_mul_f32 v[208:209], v[156:157], v[208:209] op_sel_hi:[0,1]
	v_cvt_pk_bf16_f32 v207, v208, v209
	ds_write_b64 v197, v[206:207] offset:2048
	v_exp_f32_e32 v206, v151
	v_fma_f32 v151, v97, v248, -v201
	v_exp_f32_e32 v207, v151
	v_fma_f32 v151, v98, v248, -v201
	v_exp_f32_e32 v208, v151
	v_fma_f32 v151, v99, v248, -v201
	v_exp_f32_e32 v209, v151
	v_pk_mul_f32 v[206:207], v[156:157], v[206:207] op_sel_hi:[0,1]
	v_fma_f32 v151, v92, v248, -v200
	v_cvt_pk_bf16_f32 v206, v206, v207
	v_pk_mul_f32 v[208:209], v[156:157], v[208:209] op_sel_hi:[0,1]
	v_cvt_pk_bf16_f32 v207, v208, v209
	ds_write_b64 v149, v[206:207] offset:2048
	v_exp_f32_e32 v206, v151
	v_fma_f32 v151, v93, v248, -v200
	v_exp_f32_e32 v207, v151
	v_fma_f32 v151, v94, v248, -v200
	v_exp_f32_e32 v208, v151
	v_fma_f32 v151, v95, v248, -v200
	v_exp_f32_e32 v209, v151
	v_pk_mul_f32 v[206:207], v[154:155], v[206:207] op_sel_hi:[0,1]
; __device__ __forceinline__ uint2 pk4(const f32x4& v) { uint2 r; r.x = pk2(v[0], v[1]); r.y = pk2(v[2], v[3]); return r; }
; template <class F>
; __device__ __forceinline__ void epi_store_bf16(f32x4 (&acc)[8][4], bf16* C, int ldc, int wr, int wc, int fr, int fq, F f) {
;     ...
;         *(uint2*)(slab + (mm * 16 + fr) * 128 + (((n * 4 + fq) ^ (fr & 14)) << 3)) = pk4(f(acc[half * 4 + mm][n], half * 4 + mm, n));
; #pragma unroll
;     for (int i = 0; i < 8; ++i) {
;       const int r = i * 8 + rr;
;       uint4 w = *(const uint4*)(slab + r * 128 + (((2 * kk) ^ (r & 14)) << 3));
;       { typedef unsigned u32x4 __attribute__((ext_vector_type(4)));
;         u32x4 wv = {w.x, w.y, w.z, w.w};
;         __builtin_amdgcn_raw_buffer_store_b128(wv, rsrc, (int)(((unsigned)((half * 64 + i * 8) * ldc) + go) * 2u), 0, 16  ); } }
	v_fma_f32 v151, v88, v248, -v200
	v_cvt_pk_bf16_f32 v206, v206, v207
	v_pk_mul_f32 v[208:209], v[154:155], v[208:209] op_sel_hi:[0,1]
	v_cvt_pk_bf16_f32 v207, v208, v209
	ds_write_b64 v155, v[206:207] offset:4096
	v_exp_f32_e32 v206, v151
	v_fma_f32 v151, v89, v248, -v200
	v_exp_f32_e32 v207, v151
	v_fma_f32 v151, v90, v248, -v200
	v_exp_f32_e32 v208, v151
	v_fma_f32 v151, v91, v248, -v200
	v_exp_f32_e32 v209, v151
	v_pk_mul_f32 v[206:207], v[154:155], v[206:207] op_sel_hi:[0,1]
	v_fma_f32 v151, v84, v248, -v200
	v_cvt_pk_bf16_f32 v206, v206, v207
	v_pk_mul_f32 v[208:209], v[154:155], v[208:209] op_sel_hi:[0,1]
	v_cvt_pk_bf16_f32 v207, v208, v209
	ds_write_b64 v196, v[206:207] offset:4096
	v_exp_f32_e32 v206, v151
	v_fma_f32 v151, v85, v248, -v200
	v_exp_f32_e32 v207, v151
	v_fma_f32 v151, v86, v248, -v200
	v_exp_f32_e32 v208, v151
	v_fma_f32 v151, v87, v248, -v200
	v_exp_f32_e32 v209, v151
	v_pk_mul_f32 v[206:207], v[154:155], v[206:207] op_sel_hi:[0,1]
	v_fma_f32 v151, v80, v248, -v200
	v_cvt_pk_bf16_f32 v206, v206, v207
	v_pk_mul_f32 v[208:209], v[154:155], v[208:209] op_sel_hi:[0,1]
	v_cvt_pk_bf16_f32 v207, v208, v209
	ds_write_b64 v197, v[206:207] offset:4096
	v_exp_f32_e32 v206, v151
	v_fma_f32 v151, v81, v248, -v200
	v_exp_f32_e32 v207, v151
	v_fma_f32 v151, v82, v248, -v200
	v_exp_f32_e32 v208, v151
	v_fma_f32 v151, v83, v248, -v200
	v_exp_f32_e32 v209, v151
	v_fma_f32 v151, v76, v248, -v199
	v_pk_mul_f32 v[206:207], v[154:155], v[206:207] op_sel_hi:[0,1]
	v_pk_mul_f32 v[200:201], v[154:155], v[208:209] op_sel_hi:[0,1]
	v_cvt_pk_bf16_f32 v206, v206, v207
	v_cvt_pk_bf16_f32 v207, v200, v201
	v_exp_f32_e32 v200, v151
	v_fma_f32 v151, v77, v248, -v199
	v_exp_f32_e32 v201, v151
	v_fma_f32 v151, v78, v248, -v199
	ds_write_b64 v149, v[206:207] offset:4096
	v_exp_f32_e32 v206, v151
	v_fma_f32 v151, v79, v248, -v199
	v_exp_f32_e32 v207, v151
	v_pk_mul_f32 v[200:201], v[152:153], v[200:201] op_sel_hi:[0,1]
	v_fma_f32 v151, v72, v248, -v199
	v_cvt_pk_bf16_f32 v200, v200, v201
	v_pk_mul_f32 v[206:207], v[152:153], v[206:207] op_sel_hi:[0,1]
	v_cvt_pk_bf16_f32 v201, v206, v207
	ds_write_b64 v155, v[200:201] offset:6144
	v_exp_f32_e32 v200, v151
	v_fma_f32 v151, v73, v248, -v199
	v_exp_f32_e32 v201, v151
	v_fma_f32 v151, v74, v248, -v199
	v_exp_f32_e32 v206, v151
	v_fma_f32 v151, v75, v248, -v199
	v_exp_f32_e32 v207, v151
	v_pk_mul_f32 v[200:201], v[152:153], v[200:201] op_sel_hi:[0,1]
	v_fma_f32 v151, v68, v248, -v199
	v_cvt_pk_bf16_f32 v200, v200, v201
	v_pk_mul_f32 v[206:207], v[152:153], v[206:207] op_sel_hi:[0,1]
	v_cvt_pk_bf16_f32 v201, v206, v207
	ds_write_b64 v196, v[200:201] offset:6144
	v_exp_f32_e32 v200, v151
	v_fma_f32 v151, v69, v248, -v199
	v_exp_f32_e32 v201, v151
	v_fma_f32 v151, v70, v248, -v199
	v_exp_f32_e32 v206, v151
	v_fma_f32 v151, v71, v248, -v199
	v_exp_f32_e32 v207, v151
	v_pk_mul_f32 v[200:201], v[152:153], v[200:201] op_sel_hi:[0,1]
	v_fma_f32 v151, v64, v248, -v199
	v_cvt_pk_bf16_f32 v200, v200, v201
	v_pk_mul_f32 v[206:207], v[152:153], v[206:207] op_sel_hi:[0,1]
	v_cvt_pk_bf16_f32 v201, v206, v207
	ds_write_b64 v197, v[200:201] offset:6144
	v_exp_f32_e32 v200, v151
	v_fma_f32 v151, v65, v248, -v199
	v_exp_f32_e32 v201, v151
	v_fma_f32 v151, v66, v248, -v199
	v_exp_f32_e32 v206, v151
	v_fma_f32 v151, v67, v248, -v199
	v_exp_f32_e32 v207, v151
	v_pk_mul_f32 v[200:201], v[152:153], v[200:201] op_sel_hi:[0,1]
	v_cvt_pk_bf16_f32 v200, v200, v201
	v_add_u32_e32 v151, 8, v203
	v_pk_mul_f32 v[206:207], v[152:153], v[206:207] op_sel_hi:[0,1]
	v_cvt_pk_bf16_f32 v201, v206, v207
	ds_write_b64 v149, v[200:201] offset:6144
	ds_read_b128 v[206:209], v153
	v_lshl_add_u32 v147, v147, 7, v205
	v_lshl_add_u32 v152, v151, 7, v202
	v_lshlrev_b32_e32 v151, 3, v151
	v_and_or_b32 v147, v145, s44, v147
	v_xor_b32_e32 v151, v151, v145
	v_lshl_add_u32 v147, v203, 11, v147
	v_and_or_b32 v151, v151, s44, v152
	s_waitcnt lgkmcnt(0)
	buffer_store_dwordx4 v[206:209], v147, s[16:19], 0 offen sc1
	ds_read_b128 v[204:207], v151
	v_add_u32_e32 v152, 0x4000, v147
	s_waitcnt lgkmcnt(0)
	buffer_store_dwordx4 v[204:207], v152, s[16:19], 0 offen sc1
	ds_read_b128 v[204:207], v153 offset:2048
	v_add_u32_e32 v152, 0x8000, v147
	s_waitcnt lgkmcnt(0)
	buffer_store_dwordx4 v[204:207], v152, s[16:19], 0 offen sc1
	v_add_u32_e32 v152, 24, v203
	v_lshl_add_u32 v154, v152, 7, v202
	v_lshlrev_b32_e32 v152, 3, v152
	v_xor_b32_e32 v152, v152, v145
	v_and_or_b32 v152, v152, s44, v154
	ds_read_b128 v[204:207], v152
	v_add_u32_e32 v154, 0xc000, v147
	s_waitcnt lgkmcnt(0)
	buffer_store_dwordx4 v[204:207], v154, s[16:19], 0 offen sc1
	ds_read_b128 v[204:207], v153 offset:4096
	v_add_u32_e32 v154, 0x10000, v147
	s_waitcnt lgkmcnt(0)
	buffer_store_dwordx4 v[204:207], v154, s[16:19], 0 offen sc1
	v_add_u32_e32 v154, 40, v203
	v_lshl_add_u32 v156, v154, 7, v202
	v_lshlrev_b32_e32 v154, 3, v154
	v_xor_b32_e32 v154, v154, v145
	v_and_or_b32 v154, v154, s44, v156
	ds_read_b128 v[204:207], v154
	v_add_u32_e32 v156, 0x14000, v147
	s_waitcnt lgkmcnt(0)
	buffer_store_dwordx4 v[204:207], v156, s[16:19], 0 offen sc1
	ds_read_b128 v[204:207], v153 offset:6144
	v_add_u32_e32 v156, 0x18000, v147
	s_waitcnt lgkmcnt(0)
	buffer_store_dwordx4 v[204:207], v156, s[16:19], 0 offen sc1
	v_add_u32_e32 v156, 56, v203
	v_lshl_add_u32 v158, v156, 7, v202
	v_lshlrev_b32_e32 v156, 3, v156
	v_xor_b32_e32 v145, v156, v145
	v_and_or_b32 v145, v145, s44, v158
	ds_read_b128 v[200:203], v145
	v_add_u32_e32 v156, 0x1c000, v147
	s_waitcnt lgkmcnt(0)
; __device__ __forceinline__ uint2 pk4(const f32x4& v) { uint2 r; r.x = pk2(v[0], v[1]); r.y = pk2(v[2], v[3]); return r; }
; template <class F>
; __device__ __forceinline__ void epi_store_bf16(f32x4 (&acc)[8][4], bf16* C, int ldc, int wr, int wc, int fr, int fq, F f) {
;     ...
;       for (int n = 0; n < 4; ++n)
;         *(uint2*)(slab + (mm * 16 + fr) * 128 + (((n * 4 + fq) ^ (fr & 14)) << 3)) = pk4(f(acc[half * 4 + mm][n], half * 4 + mm, n));
	buffer_store_dwordx4 v[200:203], v156, s[16:19], 0 offen sc1
	v_fma_f32 v156, v60, v248, -v198
	v_exp_f32_e32 v200, v156
	v_fma_f32 v156, v61, v248, -v198
	v_exp_f32_e32 v201, v156
	v_fma_f32 v156, v62, v248, -v198
	v_exp_f32_e32 v202, v156
	v_fma_f32 v156, v63, v248, -v198
	v_exp_f32_e32 v203, v156
	v_pk_mul_f32 v[200:201], v[150:151], v[200:201] op_sel_hi:[0,1]
	v_fma_f32 v156, v56, v248, -v198
	v_cvt_pk_bf16_f32 v200, v200, v201
	v_pk_mul_f32 v[202:203], v[150:151], v[202:203] op_sel_hi:[0,1]
	v_cvt_pk_bf16_f32 v201, v202, v203
	ds_write_b64 v155, v[200:201]
	v_exp_f32_e32 v200, v156
	v_fma_f32 v156, v57, v248, -v198
	v_exp_f32_e32 v201, v156
	v_fma_f32 v156, v58, v248, -v198
	v_exp_f32_e32 v202, v156
	v_fma_f32 v156, v59, v248, -v198
	v_exp_f32_e32 v203, v156
	v_pk_mul_f32 v[200:201], v[150:151], v[200:201] op_sel_hi:[0,1]
	v_fma_f32 v156, v52, v248, -v198
	v_cvt_pk_bf16_f32 v200, v200, v201
	v_pk_mul_f32 v[202:203], v[150:151], v[202:203] op_sel_hi:[0,1]
	v_cvt_pk_bf16_f32 v201, v202, v203
	ds_write_b64 v196, v[200:201]
	v_exp_f32_e32 v200, v156
	v_fma_f32 v156, v53, v248, -v198
	v_exp_f32_e32 v201, v156
	v_fma_f32 v156, v54, v248, -v198
	v_exp_f32_e32 v202, v156
	v_fma_f32 v156, v55, v248, -v198
	v_exp_f32_e32 v203, v156
	v_pk_mul_f32 v[200:201], v[150:151], v[200:201] op_sel_hi:[0,1]
	v_fma_f32 v156, v48, v248, -v198
	v_cvt_pk_bf16_f32 v200, v200, v201
	v_pk_mul_f32 v[202:203], v[150:151], v[202:203] op_sel_hi:[0,1]
	v_cvt_pk_bf16_f32 v201, v202, v203
	ds_write_b64 v197, v[200:201]
	v_exp_f32_e32 v200, v156
	v_fma_f32 v156, v49, v248, -v198
	v_exp_f32_e32 v201, v156
	v_fma_f32 v156, v50, v248, -v198
	v_exp_f32_e32 v202, v156
	v_fma_f32 v156, v51, v248, -v198
	v_exp_f32_e32 v203, v156
	v_pk_mul_f32 v[200:201], v[150:151], v[200:201] op_sel_hi:[0,1]
	v_cvt_pk_bf16_f32 v200, v200, v201
	v_pk_mul_f32 v[198:199], v[150:151], v[202:203] op_sel_hi:[0,1]
	v_fma_f32 v150, v44, v248, -v160
	v_cvt_pk_bf16_f32 v201, v198, v199
	v_exp_f32_e32 v198, v150
	v_fma_f32 v150, v45, v248, -v160
	v_exp_f32_e32 v199, v150
	v_fma_f32 v150, v46, v248, -v160
	ds_write_b64 v149, v[200:201]
	v_exp_f32_e32 v200, v150
	v_fma_f32 v150, v47, v248, -v160
	v_exp_f32_e32 v201, v150
	v_pk_mul_f32 v[198:199], v[148:149], v[198:199] op_sel_hi:[0,1]
	v_fma_f32 v150, v40, v248, -v160
	v_cvt_pk_bf16_f32 v198, v198, v199
	v_pk_mul_f32 v[200:201], v[148:149], v[200:201] op_sel_hi:[0,1]
	v_cvt_pk_bf16_f32 v199, v200, v201
	ds_write_b64 v155, v[198:199] offset:2048
	v_exp_f32_e32 v198, v150
	v_fma_f32 v150, v41, v248, -v160
	v_exp_f32_e32 v199, v150
	v_fma_f32 v150, v42, v248, -v160
	v_exp_f32_e32 v200, v150
	v_fma_f32 v150, v43, v248, -v160
	v_exp_f32_e32 v201, v150
	v_pk_mul_f32 v[198:199], v[148:149], v[198:199] op_sel_hi:[0,1]
	v_fma_f32 v150, v36, v248, -v160
	v_cvt_pk_bf16_f32 v198, v198, v199
	v_pk_mul_f32 v[200:201], v[148:149], v[200:201] op_sel_hi:[0,1]
	v_cvt_pk_bf16_f32 v199, v200, v201
	ds_write_b64 v196, v[198:199] offset:2048
	v_exp_f32_e32 v198, v150
	v_fma_f32 v150, v37, v248, -v160
	v_exp_f32_e32 v199, v150
	v_fma_f32 v150, v38, v248, -v160
	v_exp_f32_e32 v200, v150
	v_fma_f32 v150, v39, v248, -v160
	v_exp_f32_e32 v201, v150
	v_pk_mul_f32 v[198:199], v[148:149], v[198:199] op_sel_hi:[0,1]
	v_fma_f32 v150, v32, v248, -v160
	v_cvt_pk_bf16_f32 v198, v198, v199
	v_pk_mul_f32 v[200:201], v[148:149], v[200:201] op_sel_hi:[0,1]
	v_cvt_pk_bf16_f32 v199, v200, v201
	ds_write_b64 v197, v[198:199] offset:2048
	v_exp_f32_e32 v198, v150
	v_fma_f32 v150, v33, v248, -v160
	v_exp_f32_e32 v199, v150
	v_fma_f32 v150, v34, v248, -v160
	v_exp_f32_e32 v200, v150
	v_fma_f32 v150, v35, v248, -v160
	v_exp_f32_e32 v201, v150
	v_pk_mul_f32 v[198:199], v[148:149], v[198:199] op_sel_hi:[0,1]
	v_cvt_pk_bf16_f32 v198, v198, v199
	v_pk_mul_f32 v[200:201], v[148:149], v[200:201] op_sel_hi:[0,1]
	v_fma_f32 v148, v28, v248, -v159
	v_cvt_pk_bf16_f32 v199, v200, v201
	ds_write_b64 v149, v[198:199] offset:2048
	v_exp_f32_e32 v198, v148
	v_fma_f32 v148, v29, v248, -v159
	v_exp_f32_e32 v199, v148
	v_fma_f32 v148, v30, v248, -v159
	v_exp_f32_e32 v200, v148
	v_fma_f32 v148, v31, v248, -v159
	v_exp_f32_e32 v201, v148
	v_pk_mul_f32 v[198:199], v[146:147], v[198:199] op_sel_hi:[0,1]
	v_fma_f32 v148, v24, v248, -v159
	v_cvt_pk_bf16_f32 v198, v198, v199
	v_pk_mul_f32 v[200:201], v[146:147], v[200:201] op_sel_hi:[0,1]
	v_cvt_pk_bf16_f32 v199, v200, v201
	ds_write_b64 v155, v[198:199] offset:4096
	v_exp_f32_e32 v198, v148
	v_fma_f32 v148, v25, v248, -v159
	v_exp_f32_e32 v199, v148
; #define RAW_BARRIER() do { asm volatile("s_waitcnt lgkmcnt(0)" ::: "memory"); __builtin_amdgcn_s_barrier(); } while (0)
; __device__ __forceinline__ uint2 pk4(const f32x4& v) { uint2 r; r.x = pk2(v[0], v[1]); r.y = pk2(v[2], v[3]); return r; }
; template <class F>
; __device__ __forceinline__ void epi_store_bf16(f32x4 (&acc)[8][4], bf16* C, int ldc, int wr, int wc, int fr, int fq, F f) {
;     ...
;       for (int n = 0; n < 4; ++n)
;         *(uint2*)(slab + (mm * 16 + fr) * 128 + (((n * 4 + fq) ^ (fr & 14)) << 3)) = pk4(f(acc[half * 4 + mm][n], half * 4 + mm, n));
; #pragma unroll
;     for (int i = 0; i < 8; ++i) {
;       const int r = i * 8 + rr;
;       uint4 w = *(const uint4*)(slab + r * 128 + (((2 * kk) ^ (r & 14)) << 3));
;       { typedef unsigned u32x4 __attribute__((ext_vector_type(4)));
;         u32x4 wv = {w.x, w.y, w.z, w.w};
;         __builtin_amdgcn_raw_buffer_store_b128(wv, rsrc, (int)(((unsigned)((half * 64 + i * 8) * ldc) + go) * 2u), 0, 16  ); } }
;   }
;   RAW_BARRIER();
	v_fma_f32 v148, v26, v248, -v159
	v_exp_f32_e32 v200, v148
	v_fma_f32 v148, v27, v248, -v159
	v_exp_f32_e32 v201, v148
	v_pk_mul_f32 v[198:199], v[146:147], v[198:199] op_sel_hi:[0,1]
	v_fma_f32 v148, v20, v248, -v159
	v_cvt_pk_bf16_f32 v198, v198, v199
	v_pk_mul_f32 v[200:201], v[146:147], v[200:201] op_sel_hi:[0,1]
	v_cvt_pk_bf16_f32 v199, v200, v201
	ds_write_b64 v196, v[198:199] offset:4096
	v_exp_f32_e32 v198, v148
	v_fma_f32 v148, v21, v248, -v159
	v_exp_f32_e32 v199, v148
	v_fma_f32 v148, v22, v248, -v159
	v_exp_f32_e32 v200, v148
	v_fma_f32 v148, v23, v248, -v159
	v_exp_f32_e32 v201, v148
	v_pk_mul_f32 v[198:199], v[146:147], v[198:199] op_sel_hi:[0,1]
	v_fma_f32 v148, v16, v248, -v159
	v_cvt_pk_bf16_f32 v198, v198, v199
	v_pk_mul_f32 v[200:201], v[146:147], v[200:201] op_sel_hi:[0,1]
	v_cvt_pk_bf16_f32 v199, v200, v201
	ds_write_b64 v197, v[198:199] offset:4096
	v_exp_f32_e32 v198, v148
	v_fma_f32 v148, v17, v248, -v159
	v_exp_f32_e32 v199, v148
	v_fma_f32 v148, v18, v248, -v159
	v_exp_f32_e32 v158, v148
	v_fma_f32 v148, v19, v248, -v159
	v_exp_f32_e32 v159, v148
	v_pk_mul_f32 v[198:199], v[146:147], v[198:199] op_sel_hi:[0,1]
	v_cvt_pk_bf16_f32 v198, v198, v199
	v_pk_mul_f32 v[158:159], v[146:147], v[158:159] op_sel_hi:[0,1]
	v_fma_f32 v146, v12, v248, -v157
	v_cvt_pk_bf16_f32 v199, v158, v159
	v_exp_f32_e32 v158, v146
	v_fma_f32 v146, v13, v248, -v157
	v_exp_f32_e32 v159, v146
	v_fma_f32 v146, v14, v248, -v157
	ds_write_b64 v149, v[198:199] offset:4096
	v_exp_f32_e32 v198, v146
	v_fma_f32 v146, v15, v248, -v157
	v_exp_f32_e32 v199, v146
	v_pk_mul_f32 v[158:159], v[144:145], v[158:159] op_sel_hi:[0,1]
	v_fma_f32 v146, v8, v248, -v157
	v_cvt_pk_bf16_f32 v158, v158, v159
	v_pk_mul_f32 v[198:199], v[144:145], v[198:199] op_sel_hi:[0,1]
	v_cvt_pk_bf16_f32 v159, v198, v199
	ds_write_b64 v155, v[158:159] offset:6144
	v_exp_f32_e32 v158, v146
	v_fma_f32 v146, v9, v248, -v157
	v_exp_f32_e32 v159, v146
	v_fma_f32 v146, v10, v248, -v157
	v_exp_f32_e32 v198, v146
	v_fma_f32 v146, v11, v248, -v157
	v_exp_f32_e32 v199, v146
	v_pk_mul_f32 v[158:159], v[144:145], v[158:159] op_sel_hi:[0,1]
	v_fma_f32 v146, v4, v248, -v157
	v_cvt_pk_bf16_f32 v158, v158, v159
	v_pk_mul_f32 v[198:199], v[144:145], v[198:199] op_sel_hi:[0,1]
	v_cvt_pk_bf16_f32 v159, v198, v199
	ds_write_b64 v196, v[158:159] offset:6144
	v_exp_f32_e32 v158, v146
	v_fma_f32 v146, v5, v248, -v157
	v_exp_f32_e32 v159, v146
	v_fma_f32 v146, v6, v248, -v157
	v_exp_f32_e32 v198, v146
	v_fma_f32 v146, v7, v248, -v157
	v_exp_f32_e32 v199, v146
	v_pk_mul_f32 v[158:159], v[144:145], v[158:159] op_sel_hi:[0,1]
	v_fma_f32 v146, v0, v248, -v157
	v_cvt_pk_bf16_f32 v158, v158, v159
	v_pk_mul_f32 v[198:199], v[144:145], v[198:199] op_sel_hi:[0,1]
	v_cvt_pk_bf16_f32 v159, v198, v199
	ds_write_b64 v197, v[158:159] offset:6144
	v_exp_f32_e32 v158, v146
	v_fma_f32 v146, v1, v248, -v157
	v_exp_f32_e32 v159, v146
	v_fma_f32 v146, v2, v248, -v157
	v_exp_f32_e32 v156, v146
	v_fma_f32 v146, v3, v248, -v157
	v_exp_f32_e32 v157, v146
	v_pk_mul_f32 v[158:159], v[144:145], v[158:159] op_sel_hi:[0,1]
	v_cvt_pk_bf16_f32 v158, v158, v159
	v_pk_mul_f32 v[156:157], v[144:145], v[156:157] op_sel_hi:[0,1]
	v_cvt_pk_bf16_f32 v159, v156, v157
	ds_write_b64 v149, v[158:159] offset:6144
	ds_read_b128 v[156:159], v153
	ds_read_b128 v[148:151], v151
	v_add_u32_e32 v144, 0x20000, v147
	s_waitcnt lgkmcnt(1)
	buffer_store_dwordx4 v[156:159], v144, s[16:19], 0 offen sc1
	v_add_u32_e32 v144, 0x24000, v147
	s_waitcnt lgkmcnt(0)
	buffer_store_dwordx4 v[148:151], v144, s[16:19], 0 offen sc1
	ds_read_b128 v[148:151], v153 offset:2048
	v_add_u32_e32 v144, 0x28000, v147
	s_waitcnt lgkmcnt(0)
	buffer_store_dwordx4 v[148:151], v144, s[16:19], 0 offen sc1
	ds_read_b128 v[148:151], v152
	v_add_u32_e32 v144, 0x2c000, v147
	s_waitcnt lgkmcnt(0)
	buffer_store_dwordx4 v[148:151], v144, s[16:19], 0 offen sc1
	ds_read_b128 v[148:151], v153 offset:4096
	v_add_u32_e32 v144, 0x30000, v147
	s_waitcnt lgkmcnt(0)
	buffer_store_dwordx4 v[148:151], v144, s[16:19], 0 offen sc1
	ds_read_b128 v[148:151], v154
	v_add_u32_e32 v144, 0x34000, v147
	s_waitcnt lgkmcnt(0)
	buffer_store_dwordx4 v[148:151], v144, s[16:19], 0 offen sc1
	ds_read_b128 v[148:151], v153 offset:6144
	v_add_u32_e32 v144, 0x38000, v147
	s_waitcnt lgkmcnt(0)
	buffer_store_dwordx4 v[148:151], v144, s[16:19], 0 offen sc1
	ds_read_b128 v[148:151], v145
	v_add_u32_e32 v144, 0x3c000, v147
	s_waitcnt lgkmcnt(0)
	buffer_store_dwordx4 v[148:151], v144, s[16:19], 0 offen sc1
	s_waitcnt lgkmcnt(0)
	s_barrier
